# FoX: segment totals preloaded into one VGPR before the key loop (no load + vmcnt(0) inside the loop)
# baseline (speedup 1.0000x reference)
; #define LAS __attribute__((address_space(3)))
; __device__ __forceinline__ void attn_mfma_item(const bf16* u, bf16* y, const float* cl, const float* tot, LAS unsigned char* wl, int item, int lane) {
;     ...
;     const float clt = fox ? clh[t] : 0.f;
;     LAS float* gl = (LAS float*)(wl + 4608);
;     const int trbase = (4 * hi + ((lane >> 2) & 3)) * PV64 + (16 * ((lane >> 4) & 1) + 4 * (lane & 3)) * 2;
;     const unsigned lane_off = (unsigned)((lane >> 3) * NU + 8 * (lane & 7)) * 2u;
;     v4u kn[4], vn[4]; float gn = 0.f;
;     { const char* tb = ubc + (size_t)(qb * 32) * NU * 2;
; #pragma unroll
;       for (int i = 0; i < 4; ++i) { kn[i] = *(const v4u*)(tb + (size_t)(8 * i * NU + koff) * 2 + lane_off); vn[i] = *(const v4u*)(tb + (size_t)(8 * i * NU + voff) * 2 + lane_off); }
;       if (fox) gn = clh[qb * 32 + r]; }
.LBB0_743:
	s_lshl_b64 s[52:53], s[52:53], 2
	v_readlane_b32 s56, v253, 16
	v_readlane_b32 s57, v253, 17
	s_add_u32 s52, s56, s52
	v_cndmask_b32_e64 v1, 0, 1, s[54:55]
	s_mov_b64 s[28:29], s[66:67]
	s_mov_b64 s[30:31], s[64:65]
	s_mov_b64 s[20:21], s[16:17]
	s_addc_u32 s53, s57, s53
	s_waitcnt vmcnt(12)
	v_mov_b32_e32 v135, 0
	v_cmp_ne_u32_e64 s[92:93], 1, v1
	s_andn2_b64 vcc, exec, s[54:55]
	v_ashrrev_i32_e32 v121, 31, v120
	v_mov_b32_e32 v134, 0
	s_cbranch_vccnz .LBB0_745
	s_waitcnt vmcnt(3)
	v_lshl_add_u64 v[4:5], v[120:121], 2, s[52:53]
	global_load_dword v134, v[4:5], off
	v_readlane_b32 s86, v253, 18
	v_readlane_b32 s87, v253, 19
	s_lshl_b32 s56, s94, 5
	s_add_u32 s86, s86, s56
	s_addc_u32 s87, s87, 0
	v_lshlrev_b32_e32 v251, 2, v145
	s_nop 1
	global_load_dword v251, v251, s[86:87]

; __device__ __forceinline__ void attn_mfma_item(const bf16* u, bf16* y, const float* cl, const float* tot, LAS unsigned char* wl, int item, int lane) {
;     ...
;             if (jt > 0 && ((jt - 1) >> 3) != (jt >> 3)) Doff += tot[bh * 8 + ((jt - 1) >> 3)];
.LBB0_764:
	s_movk_i32 s95, 0x1bf
	s_mov_b32 s94, 0xf000
	s_andn2_b64 vcc, exec, s[86:87]
	s_cbranch_vccnz .LBB0_767
	s_add_i32 s70, s1, -1
	s_lshr_b32 s70, s70, 3
	s_lshr_b32 s71, s1, 3
	s_cmp_eq_u32 s70, s71
	s_cbranch_scc1 .LBB0_767
	s_nop 3
	v_readlane_b32 s70, v251, s70
	s_nop 3
	v_add_f32_e32 v137, s70, v137
